# RWKV scan stage C: quarter-split state layout (lane = 16 rows x 4 key-quarters), 4x fewer LDS broadcast reads, cross-lane permlane reductions
# speedup vs baseline: 1.0483x; 1.0318x over previous
.LBB0_440:
	s_lshl_b32 s0, s84, 2
	v_lshrrev_b32_e32 v64, 6, v203
	v_lshl_add_u32 v65, v160, 1, s0
	v_or_b32_e32 v64, v65, v64
	v_ashrrev_i32_e32 v65, 31, v64
	v_lshlrev_b64 v[64:65], 14, v[64:65]
	v_lshl_add_u64 v[64:65], s[92:93], 0, v[64:65]
	v_and_b32_e32 v196, 15, v202
	v_lshlrev_b32_e32 v196, 8, v196
	v_lshrrev_b32_e32 v66, 4, v202
	v_lshl_add_u32 v196, v66, 6, v196
	v_readlane_b32 s24, v252, 11
	v_readlane_b32 s26, v254, 40
	v_lshl_add_u64 v[64:65], v[64:65], 0, v[196:197]
	v_readlane_b32 s25, v252, 12
	v_readlane_b32 s27, v254, 41
	s_mov_b32 s30, 0xf149f2ca
	s_mov_b64 s[20:21], 0x1000
	global_store_dwordx4 v[64:65], v[0:3], off
	global_store_dwordx4 v[64:65], v[4:7], off offset:16
	global_store_dwordx4 v[64:65], v[8:11], off offset:32
	global_store_dwordx4 v[64:65], v[12:15], off offset:48
	v_lshl_add_u64 v[64:65], v[64:65], 0, s[20:21]
	global_store_dwordx4 v[64:65], v[16:19], off
	global_store_dwordx4 v[64:65], v[20:23], off offset:16
	global_store_dwordx4 v[64:65], v[24:27], off offset:32
	global_store_dwordx4 v[64:65], v[28:31], off offset:48
	v_lshl_add_u64 v[64:65], v[64:65], 0, s[20:21]
	global_store_dwordx4 v[64:65], v[32:35], off
	global_store_dwordx4 v[64:65], v[36:39], off offset:16
	global_store_dwordx4 v[64:65], v[40:43], off offset:32
	global_store_dwordx4 v[64:65], v[44:47], off offset:48
	v_lshl_add_u64 v[64:65], v[64:65], 0, s[20:21]
	global_store_dwordx4 v[64:65], v[48:51], off
	global_store_dwordx4 v[64:65], v[52:55], off offset:16
	global_store_dwordx4 v[64:65], v[56:59], off offset:32
	global_store_dwordx4 v[64:65], v[60:63], off offset:48

.LBB0_539:
	v_and_b32_e32 v196, 0xc0, v174
	v_and_b32_e32 v152, 60, v174
	v_add_u32_e32 v196, v196, v247
	v_add_u32_e32 v152, v152, v247
	ds_read_b128 v[64:67], v196 offset:20480
	ds_read_b128 v[68:71], v196 offset:20496
	ds_read_b128 v[72:75], v196 offset:20512
	ds_read_b128 v[76:79], v196 offset:20528
	v_mov_b32_e32 v144, 0
	v_mov_b32_e32 v146, 0
	v_mov_b32_e32 v148, 0
	v_mov_b32_e32 v150, 0
	s_and_saveexec_b64 s[22:23], s[4:5]
	ds_read_b32 v144, v152 offset:8192
	ds_read_b32 v146, v152 offset:8256
	ds_read_b32 v148, v152 offset:8320
	ds_read_b32 v150, v152 offset:8384
	s_or_b64 exec, exec, s[22:23]
	ds_read_b128 v[80:83], v196 offset:12288
	ds_read_b128 v[84:87], v196 offset:12304
	ds_read_b128 v[88:91], v196 offset:12320
	ds_read_b128 v[92:95], v196 offset:12336
	s_waitcnt lgkmcnt(4)
	v_pk_mul_f32 v[152:153], v[0:1], v[64:65]
	v_pk_mul_f32 v[154:155], v[16:17], v[64:65]
	v_pk_mul_f32 v[156:157], v[32:33], v[64:65]
	v_pk_mul_f32 v[158:159], v[48:49], v[64:65]
	ds_read_b128 v[96:99], v196 offset:16384
	ds_read_b128 v[100:103], v196 offset:16400
	v_pk_fma_f32 v[152:153], v[2:3], v[66:67], v[152:153]
	v_pk_fma_f32 v[154:155], v[18:19], v[66:67], v[154:155]
	v_pk_fma_f32 v[156:157], v[34:35], v[66:67], v[156:157]
	v_pk_fma_f32 v[158:159], v[50:51], v[66:67], v[158:159]
	ds_read_b128 v[104:107], v196 offset:16416
	ds_read_b128 v[108:111], v196 offset:16432
	v_pk_fma_f32 v[152:153], v[4:5], v[68:69], v[152:153]
	v_pk_fma_f32 v[154:155], v[20:21], v[68:69], v[154:155]
	v_pk_fma_f32 v[156:157], v[36:37], v[68:69], v[156:157]
	v_pk_fma_f32 v[158:159], v[52:53], v[68:69], v[158:159]
	ds_read_b128 v[112:115], v196 offset:4096
	ds_read_b128 v[116:119], v196 offset:4112
	v_pk_fma_f32 v[152:153], v[6:7], v[70:71], v[152:153]
	v_pk_fma_f32 v[154:155], v[22:23], v[70:71], v[154:155]
	v_pk_fma_f32 v[156:157], v[38:39], v[70:71], v[156:157]
	v_pk_fma_f32 v[158:159], v[54:55], v[70:71], v[158:159]
	ds_read_b128 v[120:123], v196 offset:4128
	ds_read_b128 v[124:127], v196 offset:4144
	v_pk_fma_f32 v[152:153], v[8:9], v[72:73], v[152:153]
	v_pk_fma_f32 v[154:155], v[24:25], v[72:73], v[154:155]
	v_pk_fma_f32 v[156:157], v[40:41], v[72:73], v[156:157]
	v_pk_fma_f32 v[158:159], v[56:57], v[72:73], v[158:159]
	ds_read_b128 v[128:131], v196 offset:0
	ds_read_b128 v[132:135], v196 offset:16
	v_pk_fma_f32 v[152:153], v[10:11], v[74:75], v[152:153]
	v_pk_fma_f32 v[154:155], v[26:27], v[74:75], v[154:155]
	v_pk_fma_f32 v[156:157], v[42:43], v[74:75], v[156:157]
	v_pk_fma_f32 v[158:159], v[58:59], v[74:75], v[158:159]
	ds_read_b128 v[136:139], v196 offset:32
	ds_read_b128 v[140:143], v196 offset:48
	v_pk_fma_f32 v[152:153], v[12:13], v[76:77], v[152:153]
	v_pk_fma_f32 v[154:155], v[28:29], v[76:77], v[154:155]
	v_pk_fma_f32 v[156:157], v[44:45], v[76:77], v[156:157]
	v_pk_fma_f32 v[158:159], v[60:61], v[76:77], v[158:159]
	v_pk_fma_f32 v[152:153], v[14:15], v[78:79], v[152:153]
	v_pk_fma_f32 v[154:155], v[30:31], v[78:79], v[154:155]
	v_pk_fma_f32 v[156:157], v[46:47], v[78:79], v[156:157]
	v_pk_fma_f32 v[158:159], v[62:63], v[78:79], v[158:159]
	v_add_f32_e32 v152, v152, v153
	v_add_f32_e32 v154, v154, v155
	v_add_f32_e32 v156, v156, v157
	v_add_f32_e32 v158, v158, v159
	s_nop 0
	v_permlane16_swap_b32_e32 v152, v154
	v_permlane16_swap_b32_e32 v156, v158
	v_add_f32_e32 v152, v152, v154
	v_add_f32_e32 v156, v156, v158
	s_nop 1
	v_permlane32_swap_b32_e32 v152, v156
	v_add_f32_e32 v152, v152, v156
	v_mov_b32_e32 v154, v152
	s_nop 1
	v_permlane16_swap_b32_e32 v152, v154
	v_mov_b32_e32 v156, v152
	v_mov_b32_e32 v158, v154
	s_nop 1
	v_permlane32_swap_b32_e32 v152, v156
	v_permlane32_swap_b32_e32 v154, v158
	s_waitcnt lgkmcnt(0)
	v_pk_mul_f32 v[0:1], v[0:1], v[80:81]
	v_pk_mul_f32 v[16:17], v[16:17], v[80:81]
	v_pk_mul_f32 v[32:33], v[32:33], v[80:81]
	v_pk_mul_f32 v[48:49], v[48:49], v[80:81]
	v_pk_fma_f32 v[0:1], v[152:153], v[96:97], v[0:1] op_sel_hi:[0,1,1] neg_lo:[1,0,0] neg_hi:[1,0,0]
	v_pk_fma_f32 v[16:17], v[154:155], v[96:97], v[16:17] op_sel_hi:[0,1,1] neg_lo:[1,0,0] neg_hi:[1,0,0]
	v_pk_fma_f32 v[32:33], v[156:157], v[96:97], v[32:33] op_sel_hi:[0,1,1] neg_lo:[1,0,0] neg_hi:[1,0,0]
	v_pk_fma_f32 v[48:49], v[158:159], v[96:97], v[48:49] op_sel_hi:[0,1,1] neg_lo:[1,0,0] neg_hi:[1,0,0]
	v_pk_fma_f32 v[0:1], v[144:145], v[112:113], v[0:1] op_sel_hi:[0,1,1]
	v_pk_fma_f32 v[16:17], v[146:147], v[112:113], v[16:17] op_sel_hi:[0,1,1]
	v_pk_fma_f32 v[32:33], v[148:149], v[112:113], v[32:33] op_sel_hi:[0,1,1]
	v_pk_fma_f32 v[48:49], v[150:151], v[112:113], v[48:49] op_sel_hi:[0,1,1]
	v_pk_mul_f32 v[230:231], v[0:1], v[128:129]
	v_pk_mul_f32 v[232:233], v[16:17], v[128:129]
	v_pk_mul_f32 v[248:249], v[32:33], v[128:129]
	v_pk_mul_f32 v[250:251], v[48:49], v[128:129]
	v_pk_mul_f32 v[2:3], v[2:3], v[82:83]
	v_pk_mul_f32 v[18:19], v[18:19], v[82:83]
	v_pk_mul_f32 v[34:35], v[34:35], v[82:83]
	v_pk_mul_f32 v[50:51], v[50:51], v[82:83]
	v_pk_fma_f32 v[2:3], v[152:153], v[98:99], v[2:3] op_sel_hi:[0,1,1] neg_lo:[1,0,0] neg_hi:[1,0,0]
	v_pk_fma_f32 v[18:19], v[154:155], v[98:99], v[18:19] op_sel_hi:[0,1,1] neg_lo:[1,0,0] neg_hi:[1,0,0]
	v_pk_fma_f32 v[34:35], v[156:157], v[98:99], v[34:35] op_sel_hi:[0,1,1] neg_lo:[1,0,0] neg_hi:[1,0,0]
	v_pk_fma_f32 v[50:51], v[158:159], v[98:99], v[50:51] op_sel_hi:[0,1,1] neg_lo:[1,0,0] neg_hi:[1,0,0]
	v_pk_fma_f32 v[2:3], v[144:145], v[114:115], v[2:3] op_sel_hi:[0,1,1]
	v_pk_fma_f32 v[18:19], v[146:147], v[114:115], v[18:19] op_sel_hi:[0,1,1]
	v_pk_fma_f32 v[34:35], v[148:149], v[114:115], v[34:35] op_sel_hi:[0,1,1]
	v_pk_fma_f32 v[50:51], v[150:151], v[114:115], v[50:51] op_sel_hi:[0,1,1]
	v_pk_fma_f32 v[230:231], v[2:3], v[130:131], v[230:231]
	v_pk_fma_f32 v[232:233], v[18:19], v[130:131], v[232:233]
	v_pk_fma_f32 v[248:249], v[34:35], v[130:131], v[248:249]
	v_pk_fma_f32 v[250:251], v[50:51], v[130:131], v[250:251]
	v_pk_mul_f32 v[4:5], v[4:5], v[84:85]
	v_pk_mul_f32 v[20:21], v[20:21], v[84:85]
	v_pk_mul_f32 v[36:37], v[36:37], v[84:85]
	v_pk_mul_f32 v[52:53], v[52:53], v[84:85]
	v_pk_fma_f32 v[4:5], v[152:153], v[100:101], v[4:5] op_sel_hi:[0,1,1] neg_lo:[1,0,0] neg_hi:[1,0,0]
	v_pk_fma_f32 v[20:21], v[154:155], v[100:101], v[20:21] op_sel_hi:[0,1,1] neg_lo:[1,0,0] neg_hi:[1,0,0]
	v_pk_fma_f32 v[36:37], v[156:157], v[100:101], v[36:37] op_sel_hi:[0,1,1] neg_lo:[1,0,0] neg_hi:[1,0,0]
	v_pk_fma_f32 v[52:53], v[158:159], v[100:101], v[52:53] op_sel_hi:[0,1,1] neg_lo:[1,0,0] neg_hi:[1,0,0]
	v_pk_fma_f32 v[4:5], v[144:145], v[116:117], v[4:5] op_sel_hi:[0,1,1]
	v_pk_fma_f32 v[20:21], v[146:147], v[116:117], v[20:21] op_sel_hi:[0,1,1]
	v_pk_fma_f32 v[36:37], v[148:149], v[116:117], v[36:37] op_sel_hi:[0,1,1]
	v_pk_fma_f32 v[52:53], v[150:151], v[116:117], v[52:53] op_sel_hi:[0,1,1]
	v_pk_fma_f32 v[230:231], v[4:5], v[132:133], v[230:231]
	v_pk_fma_f32 v[232:233], v[20:21], v[132:133], v[232:233]
	v_pk_fma_f32 v[248:249], v[36:37], v[132:133], v[248:249]
	v_pk_fma_f32 v[250:251], v[52:53], v[132:133], v[250:251]
	v_pk_mul_f32 v[6:7], v[6:7], v[86:87]
	v_pk_mul_f32 v[22:23], v[22:23], v[86:87]
	v_pk_mul_f32 v[38:39], v[38:39], v[86:87]
	v_pk_mul_f32 v[54:55], v[54:55], v[86:87]
	v_pk_fma_f32 v[6:7], v[152:153], v[102:103], v[6:7] op_sel_hi:[0,1,1] neg_lo:[1,0,0] neg_hi:[1,0,0]
	v_pk_fma_f32 v[22:23], v[154:155], v[102:103], v[22:23] op_sel_hi:[0,1,1] neg_lo:[1,0,0] neg_hi:[1,0,0]
	v_pk_fma_f32 v[38:39], v[156:157], v[102:103], v[38:39] op_sel_hi:[0,1,1] neg_lo:[1,0,0] neg_hi:[1,0,0]
	v_pk_fma_f32 v[54:55], v[158:159], v[102:103], v[54:55] op_sel_hi:[0,1,1] neg_lo:[1,0,0] neg_hi:[1,0,0]
	v_pk_fma_f32 v[6:7], v[144:145], v[118:119], v[6:7] op_sel_hi:[0,1,1]
	v_pk_fma_f32 v[22:23], v[146:147], v[118:119], v[22:23] op_sel_hi:[0,1,1]
	v_pk_fma_f32 v[38:39], v[148:149], v[118:119], v[38:39] op_sel_hi:[0,1,1]
	v_pk_fma_f32 v[54:55], v[150:151], v[118:119], v[54:55] op_sel_hi:[0,1,1]
	v_pk_fma_f32 v[230:231], v[6:7], v[134:135], v[230:231]
	v_pk_fma_f32 v[232:233], v[22:23], v[134:135], v[232:233]
	v_pk_fma_f32 v[248:249], v[38:39], v[134:135], v[248:249]
	v_pk_fma_f32 v[250:251], v[54:55], v[134:135], v[250:251]
	v_pk_mul_f32 v[8:9], v[8:9], v[88:89]
	v_pk_mul_f32 v[24:25], v[24:25], v[88:89]
	v_pk_mul_f32 v[40:41], v[40:41], v[88:89]
	v_pk_mul_f32 v[56:57], v[56:57], v[88:89]
	v_pk_fma_f32 v[8:9], v[152:153], v[104:105], v[8:9] op_sel_hi:[0,1,1] neg_lo:[1,0,0] neg_hi:[1,0,0]
	v_pk_fma_f32 v[24:25], v[154:155], v[104:105], v[24:25] op_sel_hi:[0,1,1] neg_lo:[1,0,0] neg_hi:[1,0,0]
	v_pk_fma_f32 v[40:41], v[156:157], v[104:105], v[40:41] op_sel_hi:[0,1,1] neg_lo:[1,0,0] neg_hi:[1,0,0]
	v_pk_fma_f32 v[56:57], v[158:159], v[104:105], v[56:57] op_sel_hi:[0,1,1] neg_lo:[1,0,0] neg_hi:[1,0,0]
	v_pk_fma_f32 v[8:9], v[144:145], v[120:121], v[8:9] op_sel_hi:[0,1,1]
	v_pk_fma_f32 v[24:25], v[146:147], v[120:121], v[24:25] op_sel_hi:[0,1,1]
	v_pk_fma_f32 v[40:41], v[148:149], v[120:121], v[40:41] op_sel_hi:[0,1,1]
	v_pk_fma_f32 v[56:57], v[150:151], v[120:121], v[56:57] op_sel_hi:[0,1,1]
	v_pk_fma_f32 v[230:231], v[8:9], v[136:137], v[230:231]
	v_pk_fma_f32 v[232:233], v[24:25], v[136:137], v[232:233]
	v_pk_fma_f32 v[248:249], v[40:41], v[136:137], v[248:249]
	v_pk_fma_f32 v[250:251], v[56:57], v[136:137], v[250:251]
	v_pk_mul_f32 v[10:11], v[10:11], v[90:91]
	v_pk_mul_f32 v[26:27], v[26:27], v[90:91]
	v_pk_mul_f32 v[42:43], v[42:43], v[90:91]
	v_pk_mul_f32 v[58:59], v[58:59], v[90:91]
	v_pk_fma_f32 v[10:11], v[152:153], v[106:107], v[10:11] op_sel_hi:[0,1,1] neg_lo:[1,0,0] neg_hi:[1,0,0]
	v_pk_fma_f32 v[26:27], v[154:155], v[106:107], v[26:27] op_sel_hi:[0,1,1] neg_lo:[1,0,0] neg_hi:[1,0,0]
	v_pk_fma_f32 v[42:43], v[156:157], v[106:107], v[42:43] op_sel_hi:[0,1,1] neg_lo:[1,0,0] neg_hi:[1,0,0]
	v_pk_fma_f32 v[58:59], v[158:159], v[106:107], v[58:59] op_sel_hi:[0,1,1] neg_lo:[1,0,0] neg_hi:[1,0,0]
	v_pk_fma_f32 v[10:11], v[144:145], v[122:123], v[10:11] op_sel_hi:[0,1,1]
	v_pk_fma_f32 v[26:27], v[146:147], v[122:123], v[26:27] op_sel_hi:[0,1,1]
	v_pk_fma_f32 v[42:43], v[148:149], v[122:123], v[42:43] op_sel_hi:[0,1,1]
	v_pk_fma_f32 v[58:59], v[150:151], v[122:123], v[58:59] op_sel_hi:[0,1,1]
	v_pk_fma_f32 v[230:231], v[10:11], v[138:139], v[230:231]
	v_pk_fma_f32 v[232:233], v[26:27], v[138:139], v[232:233]
	v_pk_fma_f32 v[248:249], v[42:43], v[138:139], v[248:249]
	v_pk_fma_f32 v[250:251], v[58:59], v[138:139], v[250:251]
	v_pk_mul_f32 v[12:13], v[12:13], v[92:93]
	v_pk_mul_f32 v[28:29], v[28:29], v[92:93]
	v_pk_mul_f32 v[44:45], v[44:45], v[92:93]
	v_pk_mul_f32 v[60:61], v[60:61], v[92:93]
	v_pk_fma_f32 v[12:13], v[152:153], v[108:109], v[12:13] op_sel_hi:[0,1,1] neg_lo:[1,0,0] neg_hi:[1,0,0]
	v_pk_fma_f32 v[28:29], v[154:155], v[108:109], v[28:29] op_sel_hi:[0,1,1] neg_lo:[1,0,0] neg_hi:[1,0,0]
	v_pk_fma_f32 v[44:45], v[156:157], v[108:109], v[44:45] op_sel_hi:[0,1,1] neg_lo:[1,0,0] neg_hi:[1,0,0]
	v_pk_fma_f32 v[60:61], v[158:159], v[108:109], v[60:61] op_sel_hi:[0,1,1] neg_lo:[1,0,0] neg_hi:[1,0,0]
	v_pk_fma_f32 v[12:13], v[144:145], v[124:125], v[12:13] op_sel_hi:[0,1,1]
	v_pk_fma_f32 v[28:29], v[146:147], v[124:125], v[28:29] op_sel_hi:[0,1,1]
	v_pk_fma_f32 v[44:45], v[148:149], v[124:125], v[44:45] op_sel_hi:[0,1,1]
	v_pk_fma_f32 v[60:61], v[150:151], v[124:125], v[60:61] op_sel_hi:[0,1,1]
	v_pk_fma_f32 v[230:231], v[12:13], v[140:141], v[230:231]
	v_pk_fma_f32 v[232:233], v[28:29], v[140:141], v[232:233]
	v_pk_fma_f32 v[248:249], v[44:45], v[140:141], v[248:249]
	v_pk_fma_f32 v[250:251], v[60:61], v[140:141], v[250:251]
	v_pk_mul_f32 v[14:15], v[14:15], v[94:95]
	v_pk_mul_f32 v[30:31], v[30:31], v[94:95]
	v_pk_mul_f32 v[46:47], v[46:47], v[94:95]
	v_pk_mul_f32 v[62:63], v[62:63], v[94:95]
	v_pk_fma_f32 v[14:15], v[152:153], v[110:111], v[14:15] op_sel_hi:[0,1,1] neg_lo:[1,0,0] neg_hi:[1,0,0]
	v_pk_fma_f32 v[30:31], v[154:155], v[110:111], v[30:31] op_sel_hi:[0,1,1] neg_lo:[1,0,0] neg_hi:[1,0,0]
	v_pk_fma_f32 v[46:47], v[156:157], v[110:111], v[46:47] op_sel_hi:[0,1,1] neg_lo:[1,0,0] neg_hi:[1,0,0]
	v_pk_fma_f32 v[62:63], v[158:159], v[110:111], v[62:63] op_sel_hi:[0,1,1] neg_lo:[1,0,0] neg_hi:[1,0,0]
	v_pk_fma_f32 v[14:15], v[144:145], v[126:127], v[14:15] op_sel_hi:[0,1,1]
	v_pk_fma_f32 v[30:31], v[146:147], v[126:127], v[30:31] op_sel_hi:[0,1,1]
	v_pk_fma_f32 v[46:47], v[148:149], v[126:127], v[46:47] op_sel_hi:[0,1,1]
	v_pk_fma_f32 v[62:63], v[150:151], v[126:127], v[62:63] op_sel_hi:[0,1,1]
	v_pk_fma_f32 v[230:231], v[14:15], v[142:143], v[230:231]
	v_pk_fma_f32 v[232:233], v[30:31], v[142:143], v[232:233]
	v_pk_fma_f32 v[248:249], v[46:47], v[142:143], v[248:249]
	v_pk_fma_f32 v[250:251], v[62:63], v[142:143], v[250:251]
	s_add_i32 s22, s30, s2
	v_mov_b32_e32 v64, s3
	v_mov_b32_e32 v65, s22
	v_cndmask_b32_e64 v64, v64, v65, s[14:15]
	v_add_f32_e32 v230, v230, v231
	v_add_f32_e32 v232, v232, v233
	v_add_f32_e32 v248, v248, v249
	v_add_f32_e32 v250, v250, v251
	s_nop 0
	v_permlane16_swap_b32_e32 v230, v232
	v_permlane16_swap_b32_e32 v248, v250
	v_add_f32_e32 v230, v230, v232
	v_add_f32_e32 v248, v248, v250
	s_nop 1
	v_permlane32_swap_b32_e32 v230, v248
	v_add_f32_e32 v66, v230, v248
	s_and_saveexec_b64 s[22:23], s[0:1]
	s_xor_b64 s[22:23], exec, s[22:23]
	s_cbranch_execz .LBB0_543
	v_ashrrev_i32_e32 v65, 31, v64
	v_lshlrev_b64 v[64:65], 12, v[64:65]
	v_lshl_add_u64 v[64:65], v[190:191], 0, v[64:65]
	global_store_dword v[64:65], v66, off
